# NSA loop: V-fragment read bases and the half-swap index computed once per task (ds offset field selects the ring slot)
# speedup vs baseline: 1.0067x; 1.0026x over previous
; DI float sigmoidf_(float x) { return __builtin_amdgcn_rcpf(1.0f + __expf(-x)); }
; DI void fs_reset(FState& st) { st.o0 = f16zero(); st.o1 = f16zero(); st.m = NINF; st.l = 0.f; }
; #define NSA_LOADT(it_, KR, VR) do { const int i_ = (it_); if (i_ < ntot) { const bool s_ = i_ < nsel; const int j_ = s_ ? i_ : c - (i_ - nsel); const bf16_t* p_ = sbase + (size_t)(64 * j_) * NZ; \
;         KR = *(const u32x4*)(p_ + (s_ ? ZC_KS : ZC_KW)); VR = *(const u32x4*)(p_ + (s_ ? ZC_VS : ZC_VW)); } } while (0)
; DI void nsa_task(LAS unsigned char* lds, const bf16_t* Z, const unsigned* selm, const bf16_t* OCMP, bf16_t* YA, int b, int hk, int c, int tid, int wave, int lane) {
;     ...
;     const float g_cmp = sigmoidf_(bf2f(zr[ZC_GA + head])), g_slc = sigmoidf_(bf2f(zr[ZC_GA + 8 + head])), g_win = sigmoidf_(bf2f(zr[ZC_GA + 16 + head]));
;     f32x16 y0 = f16zero(), y1 = f16zero();
;     FState st; fs_reset(st);
;     const int nsel = EN_SLC ? c + 1 : 0, nwin = EN_WIN ? (c + 1 < 9 ? c + 1 : 9) : 0, ntot = nsel + nwin;
;     const int skey = tid >> 3, sch = tid & 7;
;     const int kdst = skey * 128 + ((sch ^ ((skey >> 1) & 7)) << 4), vdst = 8192 + skey * 128 + ((sch * 16) ^ (((skey >> 1) & 1) << 6));
;     const bf16_t* sbase = Z + ((size_t)b * SEQ + skey) * NZ + hk * 64 + sch * 8;
;     u32x4 kA = {0u, 0u, 0u, 0u}, vA = kA, kB = kA, vB = kA, kC = kA, vC = kA;
;     ...
;     NSA_LOADT(0, kA, vA); NSA_LOADT(1, kB, vB); NSA_LOADT(2, kC, vC);
;     for (int it0 = 0; it0 < ntot; it0 += 3) {
;         NSA_STEP(it0, kA, vA);
.LBB0_740:
	s_waitcnt vmcnt(3)
	v_lshlrev_b32_e32 v5, 16, v5
	v_mul_f32_e32 v5, 0xbfb8aa3b, v5
	v_exp_f32_e32 v5, v5
	v_lshlrev_b32_e32 v195, 6, v4
	v_lshlrev_b32_e32 v4, 7, v194
	v_lshlrev_b32_e32 v6, 4, v205
	v_add_f32_e32 v5, 1.0, v5
	v_rcp_f32_e32 v197, v5
	v_lshlrev_b32_e32 v5, 6, v206
	v_and_b32_e32 v5, 64, v5
	v_mov_b32_e32 v16, v3
	v_mov_b32_e32 v17, v3
	v_and_or_b32 v205, v6, s66, v4
	v_lshlrev_b32_e32 v206, 4, v207
	v_lshlrev_b32_e32 v207, 4, v208
	v_lshlrev_b32_e32 v208, 4, v209
	v_lshlrev_b32_e32 v209, 4, v212
	s_add_i32 s4, s50, s69
	v_bitop3_b32 v212, v5, v4, v2 bitop3:0xde
	v_mov_b32_e32 v2, v3
	v_mov_b32_e32 v4, v3
	v_mov_b32_e32 v5, v3
	v_mov_b32_e32 v6, v3
	v_mov_b32_e32 v7, v3
	v_mov_b32_e32 v8, v3
	v_mov_b32_e32 v9, v3
	v_mov_b32_e32 v10, v3
	v_mov_b32_e32 v11, v3
	v_mov_b32_e32 v12, v3
	v_mov_b32_e32 v13, v3
	v_mov_b32_e32 v14, v3
	v_mov_b32_e32 v15, v3
	v_mov_b64_e32 v[80:81], v[16:17]
	v_mov_b64_e32 v[64:65], v[16:17]
	v_mov_b64_e32 v[48:49], v[16:17]
	v_mov_b64_e32 v[32:33], v[16:17]
	v_lshlrev_b32_e32 v194, 2, v210
	v_add_u32_e32 v210, 0xfffffe00, v190
	v_lshlrev_b32_e32 v211, 7, v211
	s_add_i32 s52, s4, -5
	s_mov_b32 s53, 0
	v_sub_u32_e32 v213, 0, v202
	s_sub_i32 s70, 0, s69
	s_add_i32 s71, s69, -2
	s_add_i32 s72, s69, -1
	v_mov_b32_e32 v214, 0
	v_mov_b32_e32 v216, 0xff800000
	s_mov_b32 s74, 0
	v_mov_b64_e32 v[78:79], v[14:15]
	v_mov_b64_e32 v[76:77], v[12:13]
	v_mov_b64_e32 v[74:75], v[10:11]
	v_mov_b64_e32 v[72:73], v[8:9]
	v_mov_b64_e32 v[70:71], v[6:7]
	v_mov_b64_e32 v[68:69], v[4:5]
	v_mov_b64_e32 v[66:67], v[2:3]
	v_mov_b64_e32 v[62:63], v[14:15]
	v_mov_b64_e32 v[60:61], v[12:13]
	v_mov_b64_e32 v[58:59], v[10:11]
	v_mov_b64_e32 v[56:57], v[8:9]
	v_mov_b64_e32 v[54:55], v[6:7]
	v_mov_b64_e32 v[52:53], v[4:5]
	v_mov_b64_e32 v[50:51], v[2:3]
	v_mov_b64_e32 v[46:47], v[14:15]
	v_mov_b64_e32 v[44:45], v[12:13]
	v_mov_b64_e32 v[42:43], v[10:11]
	v_mov_b64_e32 v[40:41], v[8:9]
	v_mov_b64_e32 v[38:39], v[6:7]
	v_mov_b64_e32 v[36:37], v[4:5]
	v_mov_b64_e32 v[34:35], v[2:3]
	v_mov_b64_e32 v[30:31], v[14:15]
	v_mov_b64_e32 v[28:29], v[12:13]
	v_mov_b64_e32 v[26:27], v[10:11]
	v_mov_b64_e32 v[24:25], v[8:9]
	v_mov_b64_e32 v[22:23], v[6:7]
	v_mov_b64_e32 v[20:21], v[4:5]
	v_mov_b64_e32 v[18:19], v[2:3]
	v_and_b32_e32 v5, 64, v198
	v_xor_b32_e32 v4, 32, v198
	v_add_u32_e32 v5, 64, v5
	v_cmp_lt_i32_e32 vcc, v4, v5
	v_cndmask_b32_e32 v4, v198, v4, vcc
	v_lshlrev_b32_e32 v215, 2, v4
	v_add3_u32 v217, v211, v203, v204
	v_add_u32_e32 v218, v217, v202
	v_add_u32_e32 v217, v217, v213
	ds_write_b128 v205, v[162:165]
	ds_write_b128 v212, v[166:169] offset:8192
	v_add_u32_e32 v221, v201, v206
	v_add_u32_e32 v222, v201, v207
	v_add_u32_e32 v223, v201, v208
	v_add_u32_e32 v224, v201, v209
	s_waitcnt lgkmcnt(0)
	s_barrier
	ds_read_b128 v[226:229], v221
	ds_read_b128 v[230:233], v221 offset:4096
	ds_read_b128 v[234:237], v222
	ds_read_b128 v[238:241], v222 offset:4096
	s_waitcnt lgkmcnt(3)
	v_mfma_f32_32x32x16_bf16 v[98:113], v[226:229], v[146:149], 0
	s_waitcnt lgkmcnt(2)
	v_mfma_f32_32x32x16_bf16 v[82:97], v[230:233], v[146:149], 0
	ds_read_b128 v[226:229], v223
	ds_read_b128 v[230:233], v223 offset:4096
	s_waitcnt lgkmcnt(3)
	v_mfma_f32_32x32x16_bf16 v[98:113], v[234:237], v[150:153], v[98:113]
	s_waitcnt lgkmcnt(2)
	v_mfma_f32_32x32x16_bf16 v[82:97], v[238:241], v[150:153], v[82:97]
	ds_read_b128 v[234:237], v224
	ds_read_b128 v[238:241], v224 offset:4096
	s_waitcnt lgkmcnt(3)
	v_mfma_f32_32x32x16_bf16 v[98:113], v[226:229], v[154:157], v[98:113]
	s_waitcnt lgkmcnt(2)
	v_mfma_f32_32x32x16_bf16 v[82:97], v[230:233], v[154:157], v[82:97]
	s_waitcnt lgkmcnt(1)
	v_mfma_f32_32x32x16_bf16 v[98:113], v[234:237], v[158:161], v[98:113]
	s_waitcnt lgkmcnt(0)
	v_mfma_f32_32x32x16_bf16 v[82:97], v[238:241], v[158:161], v[82:97]

; DI float fexp2(float x) { return __builtin_amdgcn_exp2f(x); }
; DI float half_max(float v) { return fmaxf(v, __shfl_xor(v, 32)); }
; DI void flash_pv(FState& st, f32x16& p0, f32x16& p1, bool rowon, const LAS unsigned char* vb, int lane) {
;     float mx = fmaxf(p0[0], p1[0]);
; #pragma unroll
;     for (int r = 1; r < 16; ++r) asm("v_max3_f32 %0, %1, %2, %3" : "=v"(mx) : "v"(mx), "v"(p0[r]), "v"(p1[r]));
;     mx = half_max(mx);
;     mx = rowon ? mx : NINF;
;     const bool upd = mx > st.m + THR_RAW;
;     if (__any(upd)) {
;         const float mn = upd ? mx : st.m;
;         const float alpha = upd ? fexp2((st.m - mn) * SM_C) : 1.0f;
;         st.m = mn; st.l *= alpha;
; #pragma unroll
;         for (int r = 0; r < 16; ++r) { st.o0[r] *= alpha; st.o1[r] *= alpha; }
;     }
.LBB0_753:
	v_max_f32_e32 v2, v82, v82
	v_max_f32_e32 v4, v98, v98
	v_max_f32_e32 v2, v4, v2
	s_waitcnt lgkmcnt(3)
	v_mfma_f32_32x32x16_bf16 v[130:145], v[226:229], v[146:149], 0
	v_max3_f32 v2, v2, v99, v83
	v_max3_f32 v2, v2, v100, v84
	s_waitcnt lgkmcnt(2)
	v_mfma_f32_32x32x16_bf16 v[114:129], v[230:233], v[146:149], 0
	ds_read_b128 v[226:229], v223 offset:16384
	ds_read_b128 v[230:233], v223 offset:20480
	v_max3_f32 v2, v2, v101, v85
	v_max3_f32 v2, v2, v102, v86
	s_waitcnt lgkmcnt(3)
	v_mfma_f32_32x32x16_bf16 v[130:145], v[234:237], v[150:153], v[130:145]
	v_max3_f32 v2, v2, v103, v87
	v_max3_f32 v2, v2, v104, v88
	v_max3_f32 v2, v2, v105, v89
	s_waitcnt lgkmcnt(2)
	v_mfma_f32_32x32x16_bf16 v[114:129], v[238:241], v[150:153], v[114:129]
	ds_read_b128 v[234:237], v224 offset:16384
	ds_read_b128 v[238:241], v224 offset:20480
	v_max3_f32 v2, v2, v106, v90
	v_max3_f32 v2, v2, v107, v91
	v_max3_f32 v2, v2, v108, v92
	v_max3_f32 v2, v2, v109, v93
	v_max3_f32 v2, v2, v110, v94
	v_max3_f32 v2, v2, v111, v95
	v_max3_f32 v2, v2, v112, v96
	v_max3_f32 v2, v2, v113, v97
	v_mov_b32_e32 v4, v2
	s_nop 1
	v_permlane32_swap_b32_e32 v4, v2
	s_nop 0
	v_max_f32_e32 v2, v2, v4
	v_cndmask_b32_e64 v2, v186, v2, s[8:9]
	v_add_f32_e32 v4, 0x42317218, v216
	v_cmp_gt_f32_e32 vcc, v2, v4
	s_cbranch_vccz .LBB0_755
	s_nop 0
	v_cndmask_b32_e32 v4, v216, v2, vcc
	v_sub_f32_e32 v2, v216, v4
	v_mul_f32_e32 v2, 0x3e38aa3b, v2
	v_exp_f32_e32 v2, v2
	v_mov_b32_e32 v216, v4
	v_cndmask_b32_e32 v2, 1.0, v2, vcc
	v_mul_f32_e32 v214, v214, v2
	v_pk_mul_f32 v[80:81], v[80:81], v[2:3] op_sel_hi:[1,0]
	v_pk_mul_f32 v[78:79], v[78:79], v[2:3] op_sel_hi:[1,0]
	v_pk_mul_f32 v[76:77], v[76:77], v[2:3] op_sel_hi:[1,0]
	v_pk_mul_f32 v[74:75], v[74:75], v[2:3] op_sel_hi:[1,0]
	v_pk_mul_f32 v[72:73], v[72:73], v[2:3] op_sel_hi:[1,0]
	v_pk_mul_f32 v[70:71], v[70:71], v[2:3] op_sel_hi:[1,0]
	v_pk_mul_f32 v[68:69], v[68:69], v[2:3] op_sel_hi:[1,0]
	v_pk_mul_f32 v[66:67], v[66:67], v[2:3] op_sel_hi:[1,0]
	v_pk_mul_f32 v[64:65], v[64:65], v[2:3] op_sel_hi:[1,0]
	v_pk_mul_f32 v[62:63], v[62:63], v[2:3] op_sel_hi:[1,0]
	v_pk_mul_f32 v[60:61], v[60:61], v[2:3] op_sel_hi:[1,0]
	v_pk_mul_f32 v[58:59], v[58:59], v[2:3] op_sel_hi:[1,0]
	v_pk_mul_f32 v[56:57], v[56:57], v[2:3] op_sel_hi:[1,0]
	v_pk_mul_f32 v[54:55], v[54:55], v[2:3] op_sel_hi:[1,0]
	v_pk_mul_f32 v[52:53], v[52:53], v[2:3] op_sel_hi:[1,0]
	v_pk_mul_f32 v[50:51], v[50:51], v[2:3] op_sel_hi:[1,0]

; #define LAS __attribute__((address_space(3)))
; #define MFMA32(a, b, c) __builtin_amdgcn_mfma_f32_32x32x16_bf16((a), (b), (c), 0, 0, 0)
; DI float fexp2(float x) { return __builtin_amdgcn_exp2f(x); }
; DI s16x4 vtr(const LAS unsigned char* p) { return __builtin_bit_cast(s16x4, __builtin_amdgcn_ds_read_tr16_b64_v4i16((LAS v4i16_t*)p)); }
; DI void flash_pv(FState& st, f32x16& p0, f32x16& p1, bool rowon, const LAS unsigned char* vb, int lane) {
;     ...
;     const float cl = rowon ? SM_C : 0.0f;
;     const float bl = rowon ? ((st.m == NINF) ? 0.0f : -st.m * SM_C) : NINF;
;     float sum = 0.f;
; #pragma unroll
;     for (int r = 0; r < 16; ++r) { p0[r] = fexp2(__builtin_fmaf(p0[r], cl, bl)); p1[r] = fexp2(__builtin_fmaf(p1[r], cl, bl)); sum += p0[r] + p1[r]; }
;     st.l += sum;
;     const int h = lane >> 5;
;     const int vx = (((lane & 15) >> 3) & 1) * 64;
;     const LAS unsigned char* vp = vb + (4 * h + ((lane & 15) >> 2)) * 128 + ((lane >> 4) & 1) * 32 + (lane & 3) * 8;
; #pragma unroll
;     for (int sub = 0; sub < 2; ++sub)
; #pragma unroll
;         for (int s2 = 0; s2 < 2; ++s2) {
;             const bf16x8 pf = pack8h(sub ? p1 : p0, s2);
;             const LAS unsigned char* vq = vp + (32 * sub + 16 * s2) * 128;
;             { const s16x4 lo = vtr(vq + vx), hi = vtr(vq + 1024 + vx); const bf16x8 vf = {lo[0], lo[1], lo[2], lo[3], hi[0], hi[1], hi[2], hi[3]}; st.o0 = MFMA32(vf, pf, st.o0); }
;             { const s16x4 lo = vtr(vq + (64 - vx)), hi = vtr(vq + 1024 + (64 - vx)); const bf16x8 vf = {lo[0], lo[1], lo[2], lo[3], hi[0], hi[1], hi[2], hi[3]}; st.o1 = MFMA32(vf, pf, st.o1); }
;         }
.LBB0_759:
	s_or_b64 exec, exec, s[4:5]
	v_fma_f32 v2, v98, v5, v4
	v_exp_f32_e32 v12, v2
	v_fma_f32 v2, v82, v5, v4
	v_exp_f32_e32 v246, v2
	s_waitcnt lgkmcnt(3)
	v_mfma_f32_32x32x16_bf16 v[130:145], v[226:229], v[154:157], v[130:145]
	v_fma_f32 v2, v99, v5, v4
	v_exp_f32_e32 v6, v2
	v_fma_f32 v2, v83, v5, v4
	v_exp_f32_e32 v2, v2
	v_add_f32_e32 v7, v12, v246
	s_add_i32 s77, s74, 1
	s_cmp_ge_u32 s77, s51
	v_pk_add_f32 v[8:9], v[6:7], v[2:3]
	v_fma_f32 v7, v100, v5, v4
	v_pk_add_f32 v[98:99], v[8:9], v[8:9] op_sel_hi:[0,1]
	s_waitcnt lgkmcnt(2)
	v_mfma_f32_32x32x16_bf16 v[114:129], v[230:233], v[154:157], v[114:129]
	v_fma_f32 v8, v84, v5, v4
	v_exp_f32_e32 v7, v7
	v_exp_f32_e32 v247, v8
	v_fma_f32 v8, v101, v5, v4
	v_fma_f32 v9, v85, v5, v4
	v_exp_f32_e32 v8, v8
	v_exp_f32_e32 v98, v9
	v_add_f32_e32 v9, v7, v247
	v_cvt_pk_bf16_f32 v6, v12, v6
	v_cvt_pk_bf16_f32 v7, v7, v8
	s_waitcnt lgkmcnt(1)
	v_mfma_f32_32x32x16_bf16 v[130:145], v[234:237], v[158:161], v[130:145]
	v_pk_add_f32 v[10:11], v[8:9], v[98:99]
	v_fma_f32 v9, v102, v5, v4
	v_pk_add_f32 v[100:101], v[10:11], v[10:11] op_sel_hi:[0,1]
	v_fma_f32 v10, v86, v5, v4
	v_exp_f32_e32 v99, v10
	v_fma_f32 v10, v103, v5, v4
	v_exp_f32_e32 v9, v9
	v_exp_f32_e32 v14, v10
	v_fma_f32 v10, v87, v5, v4
	v_exp_f32_e32 v100, v10
	s_waitcnt lgkmcnt(0)
	v_mfma_f32_32x32x16_bf16 v[114:129], v[238:241], v[158:161], v[114:129]
	v_add_f32_e32 v15, v9, v99
	v_cvt_pk_bf16_f32 v8, v9, v14
	v_pk_add_f32 v[10:11], v[14:15], v[100:101]
	s_nop 0
	v_pk_add_f32 v[86:87], v[10:11], v[10:11] op_sel_hi:[0,1]
	v_fma_f32 v10, v104, v5, v4
	v_exp_f32_e32 v15, v10
	v_fma_f32 v10, v88, v5, v4
	v_exp_f32_e32 v101, v10
	v_fma_f32 v10, v105, v5, v4
	v_exp_f32_e32 v16, v10
	v_fma_f32 v10, v89, v5, v4
	v_exp_f32_e32 v86, v10
	v_add_f32_e32 v17, v15, v101
	v_cvt_pk_bf16_f32 v9, v15, v16
	v_pk_add_f32 v[10:11], v[16:17], v[86:87]
	s_nop 0
	v_pk_add_f32 v[88:89], v[10:11], v[10:11] op_sel_hi:[0,1]
	v_fma_f32 v10, v106, v5, v4
	v_exp_f32_e32 v87, v10
	v_fma_f32 v10, v90, v5, v4
	v_exp_f32_e32 v248, v10
	v_fma_f32 v10, v107, v5, v4
	v_exp_f32_e32 v90, v10
	v_fma_f32 v10, v91, v5, v4
	v_exp_f32_e32 v88, v10
	v_fma_f32 v10, v108, v5, v4
	v_exp_f32_e32 v107, v10
	v_fma_f32 v10, v92, v5, v4
	v_add_f32_e32 v91, v87, v248
	v_exp_f32_e32 v108, v10
	v_pk_add_f32 v[10:11], v[90:91], v[88:89]
	v_fma_f32 v91, v112, v5, v4
	v_pk_add_f32 v[102:103], v[10:11], v[10:11] op_sel_hi:[0,1]
	v_fma_f32 v10, v109, v5, v4
	v_exp_f32_e32 v104, v10
	v_fma_f32 v10, v93, v5, v4
	v_exp_f32_e32 v102, v10
	ds_read_b64_tr_b16 v[10:11], v218 offset:8192
	ds_read_b64_tr_b16 v[12:13], v218 offset:9216
	ds_read_b64_tr_b16 v[14:15], v217 offset:8256
	ds_read_b64_tr_b16 v[16:17], v217 offset:9280
	ds_read_b64_tr_b16 v[82:83], v218 offset:10240
	ds_read_b64_tr_b16 v[84:85], v218 offset:11264
	s_waitcnt lgkmcnt(4)
	v_mfma_f32_32x32x16_bf16 v[66:81], v[10:13], v[6:9], v[66:81]
	v_fma_f32 v10, v110, v5, v4
	v_exp_f32_e32 v89, v10
	v_fma_f32 v10, v111, v5, v4
	v_exp_f32_e32 v92, v10
	v_exp_f32_e32 v109, v91
	v_add_f32_e32 v105, v107, v108
	ds_read_b64_tr_b16 v[10:11], v217 offset:10304
	ds_read_b64_tr_b16 v[12:13], v217 offset:11328
	s_waitcnt lgkmcnt(4)
	v_mfma_f32_32x32x16_bf16 v[50:65], v[14:17], v[6:9], v[50:65]
	v_fma_f32 v6, v113, v5, v4
	v_exp_f32_e32 v106, v6
	v_cvt_pk_bf16_f32 v6, v87, v90
	v_cvt_pk_bf16_f32 v7, v107, v104
	v_cvt_pk_bf16_f32 v8, v89, v92
	v_cvt_pk_bf16_f32 v9, v109, v106
	v_pk_add_f32 v[14:15], v[104:105], v[102:103]
	s_waitcnt lgkmcnt(2)
	v_mfma_f32_32x32x16_bf16 v[66:81], v[82:85], v[6:9], v[66:81]
	v_add_f32_e64 v90, v14, v14
	v_add_f32_e64 v91, v14, v15
	v_fma_f32 v14, v94, v5, v4
	v_exp_f32_e32 v94, v14
	ds_read_b64_tr_b16 v[14:15], v218 offset:12288
	ds_read_b64_tr_b16 v[16:17], v218 offset:13312
	v_fma_f32 v82, v95, v5, v4
	v_exp_f32_e32 v90, v82
	v_add_f32_e32 v93, v89, v94
	s_waitcnt lgkmcnt(2)
	v_mfma_f32_32x32x16_bf16 v[50:65], v[10:13], v[6:9], v[50:65]
	v_cvt_pk_bf16_f32 v6, v246, v2
	v_cvt_pk_bf16_f32 v7, v247, v98
	v_cvt_pk_bf16_f32 v8, v99, v100
	v_cvt_pk_bf16_f32 v9, v101, v86
	ds_read_b64_tr_b16 v[10:11], v218 offset:14336
	ds_read_b64_tr_b16 v[12:13], v218 offset:15360
	v_pk_add_f32 v[82:83], v[92:93], v[90:91]
	v_fma_f32 v2, v96, v5, v4
	s_waitcnt lgkmcnt(2)
	v_mfma_f32_32x32x16_bf16 v[66:81], v[14:17], v[6:9], v[66:81]
	ds_read_b64_tr_b16 v[14:15], v217 offset:12352
	ds_read_b64_tr_b16 v[16:17], v217 offset:13376
	v_add_f32_e64 v86, v82, v82
	v_add_f32_e64 v87, v82, v83
	v_fmac_f32_e32 v4, v97, v5
	ds_read_b64_tr_b16 v[82:83], v217 offset:14400
	ds_read_b64_tr_b16 v[84:85], v217 offset:15424
	v_exp_f32_e32 v2, v2
	v_exp_f32_e32 v86, v4
	v_cvt_pk_bf16_f32 v4, v248, v88
	s_waitcnt lgkmcnt(2)
	v_mfma_f32_32x32x16_bf16 v[50:65], v[14:17], v[6:9], v[50:65]
	v_cvt_pk_bf16_f32 v5, v108, v102
	v_cvt_pk_bf16_f32 v6, v94, v90
	v_cvt_pk_bf16_f32 v7, v2, v86
	v_add_f32_e32 v107, v109, v2
	v_add_f32_e64 v8, v106, v86
	v_add_f32_e64 v9, v107, v87
	v_add_f32_e32 v2, v8, v9
	v_mfma_f32_32x32x16_bf16 v[66:81], v[10:13], v[4:7], v[66:81]
	v_add_f32_e32 v214, v214, v2
	s_waitcnt lgkmcnt(0)
	v_mfma_f32_32x32x16_bf16 v[50:65], v[82:85], v[4:7], v[50:65]
	s_cbranch_scc1 .LBB0_780
	s_movk_i32 s76, 0x4000
	s_add_i32 s4, s74, 5
	s_cmp_ge_u32 s4, s51
	s_waitcnt vmcnt(1)
	ds_write_b128 v205, v[182:185] offset:32768
	s_waitcnt vmcnt(0)
	ds_write_b128 v212, v[178:181] offset:40960
	s_waitcnt lgkmcnt(0)
	s_barrier
	s_cbranch_scc1 .LBB0_762
	s_cmp_gt_u32 s4, s69
	s_cselect_b64 s[8:9], -1, 0
	s_mov_b32 s5, s52
	s_and_b64 s[8:9], s[8:9], exec
	s_cselect_b32 s4, s5, s4
	s_cselect_b32 s16, 0x1000, s65
	s_cselect_b32 s8, s64, 0x500
	s_lshl_b32 s4, s4, 6
	s_mov_b32 s9, s17
	v_mad_i64_i32 v[4:5], s[4:5], s4, v199, v[192:193]
	v_lshl_add_u64 v[6:7], v[4:5], 0, s[8:9]
	v_lshl_add_u64 v[4:5], v[4:5], 0, s[16:17]
	global_load_dwordx4 v[182:185], v[6:7], off
	global_load_dwordx4 v[178:181], v[4:5], off

; #define LAS __attribute__((address_space(3)))
; #define MFMA32(a, b, c) __builtin_amdgcn_mfma_f32_32x32x16_bf16((a), (b), (c), 0, 0, 0)
; DI float fexp2(float x) { return __builtin_amdgcn_exp2f(x); }
; DI s16x4 vtr(const LAS unsigned char* p) { return __builtin_bit_cast(s16x4, __builtin_amdgcn_ds_read_tr16_b64_v4i16((LAS v4i16_t*)p)); }
; DI void flash_pv(FState& st, f32x16& p0, f32x16& p1, bool rowon, const LAS unsigned char* vb, int lane) {
;     ...
;     const float cl = rowon ? SM_C : 0.0f;
;     const float bl = rowon ? ((st.m == NINF) ? 0.0f : -st.m * SM_C) : NINF;
;     float sum = 0.f;
; #pragma unroll
;     for (int r = 0; r < 16; ++r) { p0[r] = fexp2(__builtin_fmaf(p0[r], cl, bl)); p1[r] = fexp2(__builtin_fmaf(p1[r], cl, bl)); sum += p0[r] + p1[r]; }
;     st.l += sum;
;     const int h = lane >> 5;
;     const int vx = (((lane & 15) >> 3) & 1) * 64;
;     const LAS unsigned char* vp = vb + (4 * h + ((lane & 15) >> 2)) * 128 + ((lane >> 4) & 1) * 32 + (lane & 3) * 8;
; #pragma unroll
;     for (int sub = 0; sub < 2; ++sub)
; #pragma unroll
;         for (int s2 = 0; s2 < 2; ++s2) {
;             const bf16x8 pf = pack8h(sub ? p1 : p0, s2);
;             const LAS unsigned char* vq = vp + (32 * sub + 16 * s2) * 128;
;             { const s16x4 lo = vtr(vq + vx), hi = vtr(vq + 1024 + vx); const bf16x8 vf = {lo[0], lo[1], lo[2], lo[3], hi[0], hi[1], hi[2], hi[3]}; st.o0 = MFMA32(vf, pf, st.o0); }
;             { const s16x4 lo = vtr(vq + (64 - vx)), hi = vtr(vq + 1024 + (64 - vx)); const bf16x8 vf = {lo[0], lo[1], lo[2], lo[3], hi[0], hi[1], hi[2], hi[3]}; st.o1 = MFMA32(vf, pf, st.o1); }
;         }
.LBB0_778:
	s_or_b64 exec, exec, s[4:5]
	v_fma_f32 v2, v130, v5, v4
	v_exp_f32_e32 v12, v2
	v_fma_f32 v2, v114, v5, v4
	v_exp_f32_e32 v246, v2
	s_waitcnt lgkmcnt(3)
	v_mfma_f32_32x32x16_bf16 v[98:113], v[226:229], v[154:157], v[98:113]
	v_fma_f32 v2, v131, v5, v4
	v_exp_f32_e32 v6, v2
	v_fma_f32 v2, v115, v5, v4
	v_exp_f32_e32 v2, v2
	v_add_f32_e32 v7, v12, v246
	v_pk_add_f32 v[8:9], v[6:7], v[2:3]
	s_nop 0
	v_pk_add_f32 v[130:131], v[8:9], v[8:9] op_sel_hi:[0,1]
	v_fma_f32 v7, v132, v5, v4
	v_fma_f32 v8, v116, v5, v4
	s_waitcnt lgkmcnt(2)
	v_mfma_f32_32x32x16_bf16 v[82:97], v[230:233], v[154:157], v[82:97]
	v_exp_f32_e32 v7, v7
	v_exp_f32_e32 v247, v8
	v_fma_f32 v8, v133, v5, v4
	v_fma_f32 v9, v117, v5, v4
	v_exp_f32_e32 v8, v8
	v_exp_f32_e32 v130, v9
	v_add_f32_e32 v9, v7, v247
	v_cvt_pk_bf16_f32 v6, v12, v6
	v_cvt_pk_bf16_f32 v7, v7, v8
	v_pk_add_f32 v[10:11], v[8:9], v[130:131]
	s_waitcnt lgkmcnt(1)
	v_mfma_f32_32x32x16_bf16 v[98:113], v[234:237], v[158:161], v[98:113]
	v_fma_f32 v9, v134, v5, v4
	v_pk_add_f32 v[132:133], v[10:11], v[10:11] op_sel_hi:[0,1]
	v_fma_f32 v10, v118, v5, v4
	v_exp_f32_e32 v131, v10
	v_fma_f32 v10, v135, v5, v4
	v_exp_f32_e32 v9, v9
	v_exp_f32_e32 v14, v10
	v_fma_f32 v10, v119, v5, v4
	v_exp_f32_e32 v132, v10
	v_add_f32_e32 v15, v9, v131
	s_waitcnt lgkmcnt(0)
	v_mfma_f32_32x32x16_bf16 v[82:97], v[238:241], v[158:161], v[82:97]
	v_cvt_pk_bf16_f32 v8, v9, v14
	v_pk_add_f32 v[10:11], v[14:15], v[132:133]
	s_nop 0
	v_pk_add_f32 v[118:119], v[10:11], v[10:11] op_sel_hi:[0,1]
	v_fma_f32 v10, v136, v5, v4
	v_exp_f32_e32 v15, v10
	v_fma_f32 v10, v120, v5, v4
	v_exp_f32_e32 v133, v10
	v_fma_f32 v10, v137, v5, v4
	v_exp_f32_e32 v16, v10
	v_fma_f32 v10, v121, v5, v4
	v_exp_f32_e32 v118, v10
	v_add_f32_e32 v17, v15, v133
	v_cvt_pk_bf16_f32 v9, v15, v16
	v_pk_add_f32 v[10:11], v[16:17], v[118:119]
	s_nop 0
	v_pk_add_f32 v[120:121], v[10:11], v[10:11] op_sel_hi:[0,1]
	v_fma_f32 v10, v138, v5, v4
	v_exp_f32_e32 v119, v10
	v_fma_f32 v10, v122, v5, v4
	v_exp_f32_e32 v248, v10
	v_fma_f32 v10, v139, v5, v4
	v_exp_f32_e32 v122, v10
	v_fma_f32 v10, v123, v5, v4
	v_exp_f32_e32 v120, v10
	v_fma_f32 v10, v140, v5, v4
	v_exp_f32_e32 v139, v10
	v_fma_f32 v10, v124, v5, v4
	v_add_f32_e32 v123, v119, v248
	v_exp_f32_e32 v140, v10
	v_pk_add_f32 v[10:11], v[122:123], v[120:121]
	v_fma_f32 v123, v144, v5, v4
	v_pk_add_f32 v[134:135], v[10:11], v[10:11] op_sel_hi:[0,1]
	v_fma_f32 v10, v141, v5, v4
	v_exp_f32_e32 v136, v10
	v_fma_f32 v10, v125, v5, v4
	v_exp_f32_e32 v134, v10
	ds_read_b64_tr_b16 v[10:11], v218 offset:24576
	ds_read_b64_tr_b16 v[12:13], v218 offset:25600
	ds_read_b64_tr_b16 v[14:15], v217 offset:24640
	ds_read_b64_tr_b16 v[16:17], v217 offset:25664
	ds_read_b64_tr_b16 v[114:115], v218 offset:26624
	ds_read_b64_tr_b16 v[116:117], v218 offset:27648
	s_waitcnt lgkmcnt(4)
	v_mfma_f32_32x32x16_bf16 v[66:81], v[10:13], v[6:9], v[66:81]
	v_fma_f32 v10, v142, v5, v4
	v_exp_f32_e32 v125, v10
	v_fma_f32 v10, v143, v5, v4
	v_exp_f32_e32 v124, v10
	v_exp_f32_e32 v142, v123
	v_add_f32_e32 v137, v139, v140
	ds_read_b64_tr_b16 v[10:11], v217 offset:26688
	ds_read_b64_tr_b16 v[12:13], v217 offset:27712
	s_waitcnt lgkmcnt(4)
	v_mfma_f32_32x32x16_bf16 v[50:65], v[14:17], v[6:9], v[50:65]
	v_fma_f32 v6, v145, v5, v4
	v_exp_f32_e32 v138, v6
	v_cvt_pk_bf16_f32 v6, v119, v122
	v_cvt_pk_bf16_f32 v7, v139, v136
	v_cvt_pk_bf16_f32 v8, v125, v124
	v_cvt_pk_bf16_f32 v9, v142, v138
	v_pk_add_f32 v[14:15], v[136:137], v[134:135]
	s_waitcnt lgkmcnt(2)
	v_mfma_f32_32x32x16_bf16 v[66:81], v[114:117], v[6:9], v[66:81]
	v_add_f32_e64 v122, v14, v14
	v_add_f32_e64 v123, v14, v15
	v_fma_f32 v14, v126, v5, v4
	v_exp_f32_e32 v126, v14
	ds_read_b64_tr_b16 v[14:15], v218 offset:28672
	ds_read_b64_tr_b16 v[16:17], v218 offset:29696
	v_fma_f32 v114, v127, v5, v4
	v_exp_f32_e32 v122, v114
	v_add_f32_e32 v125, v125, v126
	s_waitcnt lgkmcnt(2)
	v_mfma_f32_32x32x16_bf16 v[50:65], v[10:13], v[6:9], v[50:65]
	v_cvt_pk_bf16_f32 v6, v246, v2
	v_cvt_pk_bf16_f32 v7, v247, v130
	v_cvt_pk_bf16_f32 v8, v131, v132
	v_cvt_pk_bf16_f32 v9, v133, v118
	ds_read_b64_tr_b16 v[10:11], v218 offset:30720
	ds_read_b64_tr_b16 v[12:13], v218 offset:31744
	v_pk_add_f32 v[114:115], v[124:125], v[122:123]
	v_fma_f32 v2, v128, v5, v4
	s_waitcnt lgkmcnt(2)
	v_mfma_f32_32x32x16_bf16 v[66:81], v[14:17], v[6:9], v[66:81]
	ds_read_b64_tr_b16 v[14:15], v217 offset:28736
	ds_read_b64_tr_b16 v[16:17], v217 offset:29760
	v_add_f32_e64 v118, v114, v114
	v_add_f32_e64 v119, v114, v115
	v_fmac_f32_e32 v4, v129, v5
	ds_read_b64_tr_b16 v[114:115], v217 offset:30784
	ds_read_b64_tr_b16 v[116:117], v217 offset:31808
	v_exp_f32_e32 v2, v2
	v_exp_f32_e32 v118, v4
	v_cvt_pk_bf16_f32 v4, v248, v120
	s_waitcnt lgkmcnt(2)
	v_mfma_f32_32x32x16_bf16 v[50:65], v[14:17], v[6:9], v[50:65]
	v_cvt_pk_bf16_f32 v5, v140, v134
	v_cvt_pk_bf16_f32 v6, v126, v122
	v_cvt_pk_bf16_f32 v7, v2, v118
	v_add_f32_e32 v139, v142, v2
	v_add_f32_e64 v8, v138, v118
	v_add_f32_e64 v9, v139, v119
	v_add_f32_e32 v2, v8, v9
	v_mfma_f32_32x32x16_bf16 v[66:81], v[10:13], v[4:7], v[66:81]
	v_add_f32_e32 v214, v214, v2
	s_waitcnt lgkmcnt(0)
	v_mfma_f32_32x32x16_bf16 v[50:65], v[114:117], v[4:7], v[50:65]
	s_add_i32 s76, s74, 2
	s_cmp_ge_u32 s76, s51
	s_cbranch_scc0 .LBB0_781

; DI float fexp2(float x) { return __builtin_amdgcn_exp2f(x); }
; DI float half_max(float v) { return fmaxf(v, __shfl_xor(v, 32)); }
; DI void flash_pv(FState& st, f32x16& p0, f32x16& p1, bool rowon, const LAS unsigned char* vb, int lane) {
;     float mx = fmaxf(p0[0], p1[0]);
; #pragma unroll
;     for (int r = 1; r < 16; ++r) asm("v_max3_f32 %0, %1, %2, %3" : "=v"(mx) : "v"(mx), "v"(p0[r]), "v"(p1[r]));
;     mx = half_max(mx);
;     mx = rowon ? mx : NINF;
;     const bool upd = mx > st.m + THR_RAW;
;     if (__any(upd)) {
;         const float mn = upd ? mx : st.m;
;         const float alpha = upd ? fexp2((st.m - mn) * SM_C) : 1.0f;
;         st.m = mn; st.l *= alpha;
; #pragma unroll
;         for (int r = 0; r < 16; ++r) { st.o0[r] *= alpha; st.o1[r] *= alpha; }
;     }
.Lnq_753:
	v_max_f32_e32 v2, v114, v114
	v_max_f32_e32 v4, v130, v130
	v_max_f32_e32 v2, v4, v2
	s_waitcnt lgkmcnt(3)
	v_mfma_f32_32x32x16_bf16 v[98:113], v[226:229], v[146:149], 0
	v_max3_f32 v2, v2, v131, v115
	v_max3_f32 v2, v2, v132, v116
	s_waitcnt lgkmcnt(2)
	v_mfma_f32_32x32x16_bf16 v[82:97], v[230:233], v[146:149], 0
	ds_read_b128 v[226:229], v223 offset:16384
	ds_read_b128 v[230:233], v223 offset:20480
	v_max3_f32 v2, v2, v133, v117
	v_max3_f32 v2, v2, v134, v118
	s_waitcnt lgkmcnt(3)
	v_mfma_f32_32x32x16_bf16 v[98:113], v[234:237], v[150:153], v[98:113]
	v_max3_f32 v2, v2, v135, v119
	v_max3_f32 v2, v2, v136, v120
	v_max3_f32 v2, v2, v137, v121
	s_waitcnt lgkmcnt(2)
	v_mfma_f32_32x32x16_bf16 v[82:97], v[238:241], v[150:153], v[82:97]
	ds_read_b128 v[234:237], v224 offset:16384
	ds_read_b128 v[238:241], v224 offset:20480
	v_max3_f32 v2, v2, v138, v122
	v_max3_f32 v2, v2, v139, v123
	v_max3_f32 v2, v2, v140, v124
	v_max3_f32 v2, v2, v141, v125
	v_max3_f32 v2, v2, v142, v126
	v_max3_f32 v2, v2, v143, v127
	v_max3_f32 v2, v2, v144, v128
	v_max3_f32 v2, v2, v145, v129
	v_mov_b32_e32 v4, v2
	s_nop 1
	v_permlane32_swap_b32_e32 v4, v2
	s_nop 0
	v_max_f32_e32 v2, v2, v4
	v_cndmask_b32_e64 v2, v186, v2, s[8:9]
	v_add_f32_e32 v4, 0x42317218, v216
	v_cmp_gt_f32_e32 vcc, v2, v4
	s_cbranch_vccz .Lnq_755
	s_nop 0
	v_cndmask_b32_e32 v4, v216, v2, vcc
	v_sub_f32_e32 v2, v216, v4
	v_mul_f32_e32 v2, 0x3e38aa3b, v2
	v_exp_f32_e32 v2, v2
	v_mov_b32_e32 v216, v4
	v_cndmask_b32_e32 v2, 1.0, v2, vcc
	v_mul_f32_e32 v214, v214, v2
	v_pk_mul_f32 v[80:81], v[80:81], v[2:3] op_sel_hi:[1,0]
	v_pk_mul_f32 v[78:79], v[78:79], v[2:3] op_sel_hi:[1,0]
	v_pk_mul_f32 v[76:77], v[76:77], v[2:3] op_sel_hi:[1,0]
	v_pk_mul_f32 v[74:75], v[74:75], v[2:3] op_sel_hi:[1,0]
	v_pk_mul_f32 v[72:73], v[72:73], v[2:3] op_sel_hi:[1,0]
	v_pk_mul_f32 v[70:71], v[70:71], v[2:3] op_sel_hi:[1,0]
	v_pk_mul_f32 v[68:69], v[68:69], v[2:3] op_sel_hi:[1,0]
	v_pk_mul_f32 v[66:67], v[66:67], v[2:3] op_sel_hi:[1,0]
	v_pk_mul_f32 v[64:65], v[64:65], v[2:3] op_sel_hi:[1,0]
	v_pk_mul_f32 v[62:63], v[62:63], v[2:3] op_sel_hi:[1,0]
	v_pk_mul_f32 v[60:61], v[60:61], v[2:3] op_sel_hi:[1,0]
	v_pk_mul_f32 v[58:59], v[58:59], v[2:3] op_sel_hi:[1,0]
	v_pk_mul_f32 v[56:57], v[56:57], v[2:3] op_sel_hi:[1,0]
	v_pk_mul_f32 v[54:55], v[54:55], v[2:3] op_sel_hi:[1,0]
	v_pk_mul_f32 v[52:53], v[52:53], v[2:3] op_sel_hi:[1,0]
	v_pk_mul_f32 v[50:51], v[50:51], v[2:3] op_sel_hi:[1,0]

; #define LAS __attribute__((address_space(3)))
; #define MFMA32(a, b, c) __builtin_amdgcn_mfma_f32_32x32x16_bf16((a), (b), (c), 0, 0, 0)
; DI float fexp2(float x) { return __builtin_amdgcn_exp2f(x); }
; DI s16x4 vtr(const LAS unsigned char* p) { return __builtin_bit_cast(s16x4, __builtin_amdgcn_ds_read_tr16_b64_v4i16((LAS v4i16_t*)p)); }
; DI void flash_pv(FState& st, f32x16& p0, f32x16& p1, bool rowon, const LAS unsigned char* vb, int lane) {
;     ...
;     const float cl = rowon ? SM_C : 0.0f;
;     const float bl = rowon ? ((st.m == NINF) ? 0.0f : -st.m * SM_C) : NINF;
;     float sum = 0.f;
; #pragma unroll
;     for (int r = 0; r < 16; ++r) { p0[r] = fexp2(__builtin_fmaf(p0[r], cl, bl)); p1[r] = fexp2(__builtin_fmaf(p1[r], cl, bl)); sum += p0[r] + p1[r]; }
;     st.l += sum;
;     const int h = lane >> 5;
;     const int vx = (((lane & 15) >> 3) & 1) * 64;
;     const LAS unsigned char* vp = vb + (4 * h + ((lane & 15) >> 2)) * 128 + ((lane >> 4) & 1) * 32 + (lane & 3) * 8;
; #pragma unroll
;     for (int sub = 0; sub < 2; ++sub)
; #pragma unroll
;         for (int s2 = 0; s2 < 2; ++s2) {
;             const bf16x8 pf = pack8h(sub ? p1 : p0, s2);
;             const LAS unsigned char* vq = vp + (32 * sub + 16 * s2) * 128;
;             { const s16x4 lo = vtr(vq + vx), hi = vtr(vq + 1024 + vx); const bf16x8 vf = {lo[0], lo[1], lo[2], lo[3], hi[0], hi[1], hi[2], hi[3]}; st.o0 = MFMA32(vf, pf, st.o0); }
;             { const s16x4 lo = vtr(vq + (64 - vx)), hi = vtr(vq + 1024 + (64 - vx)); const bf16x8 vf = {lo[0], lo[1], lo[2], lo[3], hi[0], hi[1], hi[2], hi[3]}; st.o1 = MFMA32(vf, pf, st.o1); }
;         }
.Lnq_759:
	s_or_b64 exec, exec, s[4:5]
	v_fma_f32 v2, v130, v5, v4
	v_exp_f32_e32 v12, v2
	v_fma_f32 v2, v114, v5, v4
	v_exp_f32_e32 v246, v2
	s_waitcnt lgkmcnt(3)
	v_mfma_f32_32x32x16_bf16 v[98:113], v[226:229], v[154:157], v[98:113]
	v_fma_f32 v2, v131, v5, v4
	v_exp_f32_e32 v6, v2
	v_fma_f32 v2, v115, v5, v4
	v_exp_f32_e32 v2, v2
	v_add_f32_e32 v7, v12, v246
	s_add_i32 s77, s74, 1
	s_cmp_ge_u32 s77, s51
	v_pk_add_f32 v[8:9], v[6:7], v[2:3]
	v_fma_f32 v7, v132, v5, v4
	v_pk_add_f32 v[130:131], v[8:9], v[8:9] op_sel_hi:[0,1]
	s_waitcnt lgkmcnt(2)
	v_mfma_f32_32x32x16_bf16 v[82:97], v[230:233], v[154:157], v[82:97]
	v_fma_f32 v8, v116, v5, v4
	v_exp_f32_e32 v7, v7
	v_exp_f32_e32 v247, v8
	v_fma_f32 v8, v133, v5, v4
	v_fma_f32 v9, v117, v5, v4
	v_exp_f32_e32 v8, v8
	v_exp_f32_e32 v130, v9
	v_add_f32_e32 v9, v7, v247
	v_cvt_pk_bf16_f32 v6, v12, v6
	v_cvt_pk_bf16_f32 v7, v7, v8
	s_waitcnt lgkmcnt(1)
	v_mfma_f32_32x32x16_bf16 v[98:113], v[234:237], v[158:161], v[98:113]
	v_pk_add_f32 v[10:11], v[8:9], v[130:131]
	v_fma_f32 v9, v134, v5, v4
	v_pk_add_f32 v[132:133], v[10:11], v[10:11] op_sel_hi:[0,1]
	v_fma_f32 v10, v118, v5, v4
	v_exp_f32_e32 v131, v10
	v_fma_f32 v10, v135, v5, v4
	v_exp_f32_e32 v9, v9
	v_exp_f32_e32 v14, v10
	v_fma_f32 v10, v119, v5, v4
	v_exp_f32_e32 v132, v10
	s_waitcnt lgkmcnt(0)
	v_mfma_f32_32x32x16_bf16 v[82:97], v[238:241], v[158:161], v[82:97]
	v_add_f32_e32 v15, v9, v131
	v_cvt_pk_bf16_f32 v8, v9, v14
	v_pk_add_f32 v[10:11], v[14:15], v[132:133]
	s_nop 0
	v_pk_add_f32 v[118:119], v[10:11], v[10:11] op_sel_hi:[0,1]
	v_fma_f32 v10, v136, v5, v4
	v_exp_f32_e32 v15, v10
	v_fma_f32 v10, v120, v5, v4
	v_exp_f32_e32 v133, v10
	v_fma_f32 v10, v137, v5, v4
	v_exp_f32_e32 v16, v10
	v_fma_f32 v10, v121, v5, v4
	v_exp_f32_e32 v118, v10
	v_add_f32_e32 v17, v15, v133
	v_cvt_pk_bf16_f32 v9, v15, v16
	v_pk_add_f32 v[10:11], v[16:17], v[118:119]
	s_nop 0
	v_pk_add_f32 v[120:121], v[10:11], v[10:11] op_sel_hi:[0,1]
	v_fma_f32 v10, v138, v5, v4
	v_exp_f32_e32 v119, v10
	v_fma_f32 v10, v122, v5, v4
	v_exp_f32_e32 v248, v10
	v_fma_f32 v10, v139, v5, v4
	v_exp_f32_e32 v122, v10
	v_fma_f32 v10, v123, v5, v4
	v_exp_f32_e32 v120, v10
	v_fma_f32 v10, v140, v5, v4
	v_exp_f32_e32 v139, v10
	v_fma_f32 v10, v124, v5, v4
	v_add_f32_e32 v123, v119, v248
	v_exp_f32_e32 v140, v10
	v_pk_add_f32 v[10:11], v[122:123], v[120:121]
	v_fma_f32 v123, v144, v5, v4
	v_pk_add_f32 v[134:135], v[10:11], v[10:11] op_sel_hi:[0,1]
	v_fma_f32 v10, v141, v5, v4
	v_exp_f32_e32 v136, v10
	v_fma_f32 v10, v125, v5, v4
	v_exp_f32_e32 v134, v10
	ds_read_b64_tr_b16 v[10:11], v218 offset:8192
	ds_read_b64_tr_b16 v[12:13], v218 offset:9216
	ds_read_b64_tr_b16 v[14:15], v217 offset:8256
	ds_read_b64_tr_b16 v[16:17], v217 offset:9280
	ds_read_b64_tr_b16 v[114:115], v218 offset:10240
	ds_read_b64_tr_b16 v[116:117], v218 offset:11264
	s_waitcnt lgkmcnt(4)
	v_mfma_f32_32x32x16_bf16 v[66:81], v[10:13], v[6:9], v[66:81]
	v_fma_f32 v10, v142, v5, v4
	v_exp_f32_e32 v121, v10
	v_fma_f32 v10, v143, v5, v4
	v_exp_f32_e32 v124, v10
	v_exp_f32_e32 v141, v123
	v_add_f32_e32 v137, v139, v140
	ds_read_b64_tr_b16 v[10:11], v217 offset:10304
	ds_read_b64_tr_b16 v[12:13], v217 offset:11328
	s_waitcnt lgkmcnt(4)
	v_mfma_f32_32x32x16_bf16 v[50:65], v[14:17], v[6:9], v[50:65]
	v_fma_f32 v6, v145, v5, v4
	v_exp_f32_e32 v138, v6
	v_cvt_pk_bf16_f32 v6, v119, v122
	v_cvt_pk_bf16_f32 v7, v139, v136
	v_cvt_pk_bf16_f32 v8, v121, v124
	v_cvt_pk_bf16_f32 v9, v141, v138
	v_pk_add_f32 v[14:15], v[136:137], v[134:135]
	s_waitcnt lgkmcnt(2)
	v_mfma_f32_32x32x16_bf16 v[66:81], v[114:117], v[6:9], v[66:81]
	v_add_f32_e64 v122, v14, v14
	v_add_f32_e64 v123, v14, v15
	v_fma_f32 v14, v126, v5, v4
	v_exp_f32_e32 v126, v14
	ds_read_b64_tr_b16 v[14:15], v218 offset:12288
	ds_read_b64_tr_b16 v[16:17], v218 offset:13312
	v_fma_f32 v114, v127, v5, v4
	v_exp_f32_e32 v122, v114
	v_add_f32_e32 v125, v121, v126
	s_waitcnt lgkmcnt(2)
	v_mfma_f32_32x32x16_bf16 v[50:65], v[10:13], v[6:9], v[50:65]
	v_cvt_pk_bf16_f32 v6, v246, v2
	v_cvt_pk_bf16_f32 v7, v247, v130
	v_cvt_pk_bf16_f32 v8, v131, v132
	v_cvt_pk_bf16_f32 v9, v133, v118
	ds_read_b64_tr_b16 v[10:11], v218 offset:14336
	ds_read_b64_tr_b16 v[12:13], v218 offset:15360
	v_pk_add_f32 v[114:115], v[124:125], v[122:123]
	v_fma_f32 v2, v128, v5, v4
	s_waitcnt lgkmcnt(2)
	v_mfma_f32_32x32x16_bf16 v[66:81], v[14:17], v[6:9], v[66:81]
	ds_read_b64_tr_b16 v[14:15], v217 offset:12352
	ds_read_b64_tr_b16 v[16:17], v217 offset:13376
	v_add_f32_e64 v118, v114, v114
	v_add_f32_e64 v119, v114, v115
	v_fmac_f32_e32 v4, v129, v5
	ds_read_b64_tr_b16 v[114:115], v217 offset:14400
	ds_read_b64_tr_b16 v[116:117], v217 offset:15424
	v_exp_f32_e32 v2, v2
	v_exp_f32_e32 v118, v4
	v_cvt_pk_bf16_f32 v4, v248, v120
	s_waitcnt lgkmcnt(2)
	v_mfma_f32_32x32x16_bf16 v[50:65], v[14:17], v[6:9], v[50:65]
	v_cvt_pk_bf16_f32 v5, v140, v134
	v_cvt_pk_bf16_f32 v6, v126, v122
	v_cvt_pk_bf16_f32 v7, v2, v118
	v_add_f32_e32 v139, v141, v2
	v_add_f32_e64 v8, v138, v118
	v_add_f32_e64 v9, v139, v119
	v_add_f32_e32 v2, v8, v9
	v_mfma_f32_32x32x16_bf16 v[66:81], v[10:13], v[4:7], v[66:81]
	v_add_f32_e32 v214, v214, v2
	s_waitcnt lgkmcnt(0)
	v_mfma_f32_32x32x16_bf16 v[50:65], v[114:117], v[4:7], v[50:65]
	s_cbranch_scc1 .Lnq_780
	s_movk_i32 s76, 0x4000
	s_add_i32 s4, s74, 5
	s_cmp_ge_u32 s4, s51
	s_waitcnt vmcnt(1)
	ds_write_b128 v205, v[182:185] offset:32768
	s_waitcnt vmcnt(0)
	ds_write_b128 v212, v[178:181] offset:40960
	s_waitcnt lgkmcnt(0)
	s_barrier
	s_cbranch_scc1 .Lnq_762
	s_cmp_gt_u32 s4, s69
	s_cselect_b64 s[8:9], -1, 0
	s_mov_b32 s5, s52
	s_and_b64 s[8:9], s[8:9], exec
	s_cselect_b32 s4, s5, s4
	s_cselect_b32 s16, 0x1000, s65
	s_cselect_b32 s8, s64, 0x500
	s_lshl_b32 s4, s4, 6
	s_mov_b32 s9, s17
	v_mad_i64_i32 v[4:5], s[4:5], s4, v199, v[192:193]
	v_lshl_add_u64 v[6:7], v[4:5], 0, s[8:9]
	v_lshl_add_u64 v[4:5], v[4:5], 0, s[16:17]
	global_load_dwordx4 v[182:185], v[6:7], off
	global_load_dwordx4 v[178:181], v[4:5], off

; #define LAS __attribute__((address_space(3)))
; #define MFMA32(a, b, c) __builtin_amdgcn_mfma_f32_32x32x16_bf16((a), (b), (c), 0, 0, 0)
; DI float fexp2(float x) { return __builtin_amdgcn_exp2f(x); }
; DI s16x4 vtr(const LAS unsigned char* p) { return __builtin_bit_cast(s16x4, __builtin_amdgcn_ds_read_tr16_b64_v4i16((LAS v4i16_t*)p)); }
; DI void flash_pv(FState& st, f32x16& p0, f32x16& p1, bool rowon, const LAS unsigned char* vb, int lane) {
;     ...
;     const float cl = rowon ? SM_C : 0.0f;
;     const float bl = rowon ? ((st.m == NINF) ? 0.0f : -st.m * SM_C) : NINF;
;     float sum = 0.f;
; #pragma unroll
;     for (int r = 0; r < 16; ++r) { p0[r] = fexp2(__builtin_fmaf(p0[r], cl, bl)); p1[r] = fexp2(__builtin_fmaf(p1[r], cl, bl)); sum += p0[r] + p1[r]; }
;     st.l += sum;
;     const int h = lane >> 5;
;     const int vx = (((lane & 15) >> 3) & 1) * 64;
;     const LAS unsigned char* vp = vb + (4 * h + ((lane & 15) >> 2)) * 128 + ((lane >> 4) & 1) * 32 + (lane & 3) * 8;
; #pragma unroll
;     for (int sub = 0; sub < 2; ++sub)
; #pragma unroll
;         for (int s2 = 0; s2 < 2; ++s2) {
;             const bf16x8 pf = pack8h(sub ? p1 : p0, s2);
;             const LAS unsigned char* vq = vp + (32 * sub + 16 * s2) * 128;
;             { const s16x4 lo = vtr(vq + vx), hi = vtr(vq + 1024 + vx); const bf16x8 vf = {lo[0], lo[1], lo[2], lo[3], hi[0], hi[1], hi[2], hi[3]}; st.o0 = MFMA32(vf, pf, st.o0); }
;             { const s16x4 lo = vtr(vq + (64 - vx)), hi = vtr(vq + 1024 + (64 - vx)); const bf16x8 vf = {lo[0], lo[1], lo[2], lo[3], hi[0], hi[1], hi[2], hi[3]}; st.o1 = MFMA32(vf, pf, st.o1); }
;         }
.Lnq_778:
	s_or_b64 exec, exec, s[4:5]
	v_fma_f32 v2, v98, v5, v4
	v_exp_f32_e32 v12, v2
	v_fma_f32 v2, v82, v5, v4
	v_exp_f32_e32 v246, v2
	s_waitcnt lgkmcnt(3)
	v_mfma_f32_32x32x16_bf16 v[130:145], v[226:229], v[154:157], v[130:145]
	v_fma_f32 v2, v99, v5, v4
	v_exp_f32_e32 v6, v2
	v_fma_f32 v2, v83, v5, v4
	v_exp_f32_e32 v2, v2
	v_add_f32_e32 v7, v12, v246
	v_pk_add_f32 v[8:9], v[6:7], v[2:3]
	s_nop 0
	v_pk_add_f32 v[98:99], v[8:9], v[8:9] op_sel_hi:[0,1]
	v_fma_f32 v7, v100, v5, v4
	v_fma_f32 v8, v84, v5, v4
	s_waitcnt lgkmcnt(2)
	v_mfma_f32_32x32x16_bf16 v[114:129], v[230:233], v[154:157], v[114:129]
	v_exp_f32_e32 v7, v7
	v_exp_f32_e32 v247, v8
	v_fma_f32 v8, v101, v5, v4
	v_fma_f32 v9, v85, v5, v4
	v_exp_f32_e32 v8, v8
	v_exp_f32_e32 v98, v9
	v_add_f32_e32 v9, v7, v247
	v_cvt_pk_bf16_f32 v6, v12, v6
	v_cvt_pk_bf16_f32 v7, v7, v8
	v_pk_add_f32 v[10:11], v[8:9], v[98:99]
	s_waitcnt lgkmcnt(1)
	v_mfma_f32_32x32x16_bf16 v[130:145], v[234:237], v[158:161], v[130:145]
	v_fma_f32 v9, v102, v5, v4
	v_pk_add_f32 v[100:101], v[10:11], v[10:11] op_sel_hi:[0,1]
	v_fma_f32 v10, v86, v5, v4
	v_exp_f32_e32 v99, v10
	v_fma_f32 v10, v103, v5, v4
	v_exp_f32_e32 v9, v9
	v_exp_f32_e32 v14, v10
	v_fma_f32 v10, v87, v5, v4
	v_exp_f32_e32 v100, v10
	v_add_f32_e32 v15, v9, v99
	s_waitcnt lgkmcnt(0)
	v_mfma_f32_32x32x16_bf16 v[114:129], v[238:241], v[158:161], v[114:129]
	v_cvt_pk_bf16_f32 v8, v9, v14
	v_pk_add_f32 v[10:11], v[14:15], v[100:101]
	s_nop 0
	v_pk_add_f32 v[86:87], v[10:11], v[10:11] op_sel_hi:[0,1]
	v_fma_f32 v10, v104, v5, v4
	v_exp_f32_e32 v15, v10
	v_fma_f32 v10, v88, v5, v4
	v_exp_f32_e32 v101, v10
	v_fma_f32 v10, v105, v5, v4
	v_exp_f32_e32 v16, v10
	v_fma_f32 v10, v89, v5, v4
	v_exp_f32_e32 v86, v10
	v_add_f32_e32 v17, v15, v101
	v_cvt_pk_bf16_f32 v9, v15, v16
	v_pk_add_f32 v[10:11], v[16:17], v[86:87]
	s_nop 0
	v_pk_add_f32 v[88:89], v[10:11], v[10:11] op_sel_hi:[0,1]
	v_fma_f32 v10, v106, v5, v4
	v_exp_f32_e32 v87, v10
	v_fma_f32 v10, v90, v5, v4
	v_exp_f32_e32 v248, v10
	v_fma_f32 v10, v107, v5, v4
	v_exp_f32_e32 v90, v10
	v_fma_f32 v10, v91, v5, v4
	v_exp_f32_e32 v88, v10
	v_fma_f32 v10, v108, v5, v4
	v_exp_f32_e32 v107, v10
	v_fma_f32 v10, v92, v5, v4
	v_add_f32_e32 v91, v87, v248
	v_exp_f32_e32 v108, v10
	v_pk_add_f32 v[10:11], v[90:91], v[88:89]
	v_fma_f32 v91, v112, v5, v4
	v_pk_add_f32 v[102:103], v[10:11], v[10:11] op_sel_hi:[0,1]
	v_fma_f32 v10, v109, v5, v4
	v_exp_f32_e32 v104, v10
	v_fma_f32 v10, v93, v5, v4
	v_exp_f32_e32 v102, v10
	ds_read_b64_tr_b16 v[10:11], v218 offset:24576
	ds_read_b64_tr_b16 v[12:13], v218 offset:25600
	ds_read_b64_tr_b16 v[14:15], v217 offset:24640
	ds_read_b64_tr_b16 v[16:17], v217 offset:25664
	ds_read_b64_tr_b16 v[82:83], v218 offset:26624
	ds_read_b64_tr_b16 v[84:85], v218 offset:27648
	s_waitcnt lgkmcnt(4)
	v_mfma_f32_32x32x16_bf16 v[66:81], v[10:13], v[6:9], v[66:81]
	v_fma_f32 v10, v110, v5, v4
	v_exp_f32_e32 v93, v10
	v_fma_f32 v10, v111, v5, v4
	v_exp_f32_e32 v92, v10
	v_exp_f32_e32 v110, v91
	v_add_f32_e32 v105, v107, v108
	ds_read_b64_tr_b16 v[10:11], v217 offset:26688
	ds_read_b64_tr_b16 v[12:13], v217 offset:27712
	s_waitcnt lgkmcnt(4)
	v_mfma_f32_32x32x16_bf16 v[50:65], v[14:17], v[6:9], v[50:65]
	v_fma_f32 v6, v113, v5, v4
	v_exp_f32_e32 v106, v6
	v_cvt_pk_bf16_f32 v6, v87, v90
	v_cvt_pk_bf16_f32 v7, v107, v104
	v_cvt_pk_bf16_f32 v8, v93, v92
	v_cvt_pk_bf16_f32 v9, v110, v106
	v_pk_add_f32 v[14:15], v[104:105], v[102:103]
	s_waitcnt lgkmcnt(2)
	v_mfma_f32_32x32x16_bf16 v[66:81], v[82:85], v[6:9], v[66:81]
	v_add_f32_e64 v90, v14, v14
	v_add_f32_e64 v91, v14, v15
	v_fma_f32 v14, v94, v5, v4
	v_exp_f32_e32 v94, v14
	ds_read_b64_tr_b16 v[14:15], v218 offset:28672
	ds_read_b64_tr_b16 v[16:17], v218 offset:29696
	v_fma_f32 v82, v95, v5, v4
	v_exp_f32_e32 v90, v82
	v_add_f32_e32 v93, v93, v94
	s_waitcnt lgkmcnt(2)
	v_mfma_f32_32x32x16_bf16 v[50:65], v[10:13], v[6:9], v[50:65]
	v_cvt_pk_bf16_f32 v6, v246, v2
	v_cvt_pk_bf16_f32 v7, v247, v98
	v_cvt_pk_bf16_f32 v8, v99, v100
	v_cvt_pk_bf16_f32 v9, v101, v86
	ds_read_b64_tr_b16 v[10:11], v218 offset:30720
	ds_read_b64_tr_b16 v[12:13], v218 offset:31744
	v_pk_add_f32 v[82:83], v[92:93], v[90:91]
	v_fma_f32 v2, v96, v5, v4
	s_waitcnt lgkmcnt(2)
	v_mfma_f32_32x32x16_bf16 v[66:81], v[14:17], v[6:9], v[66:81]
	ds_read_b64_tr_b16 v[14:15], v217 offset:28736
	ds_read_b64_tr_b16 v[16:17], v217 offset:29760
	v_add_f32_e64 v86, v82, v82
	v_add_f32_e64 v87, v82, v83
	v_fmac_f32_e32 v4, v97, v5
	ds_read_b64_tr_b16 v[82:83], v217 offset:30784
	ds_read_b64_tr_b16 v[84:85], v217 offset:31808
	v_exp_f32_e32 v2, v2
	v_exp_f32_e32 v86, v4
	v_cvt_pk_bf16_f32 v4, v248, v88
	s_waitcnt lgkmcnt(2)
	v_mfma_f32_32x32x16_bf16 v[50:65], v[14:17], v[6:9], v[50:65]
	v_cvt_pk_bf16_f32 v5, v108, v102
	v_cvt_pk_bf16_f32 v6, v94, v90
	v_cvt_pk_bf16_f32 v7, v2, v86
	v_add_f32_e32 v107, v110, v2
	v_add_f32_e64 v8, v106, v86
	v_add_f32_e64 v9, v107, v87
	v_add_f32_e32 v2, v8, v9
	v_mfma_f32_32x32x16_bf16 v[66:81], v[10:13], v[4:7], v[66:81]
	v_add_f32_e32 v214, v214, v2
	s_waitcnt lgkmcnt(0)
	v_mfma_f32_32x32x16_bf16 v[50:65], v[82:85], v[4:7], v[50:65]
	s_add_i32 s76, s74, 2
	s_cmp_ge_u32 s76, s51
	s_cbranch_scc0 .Lnq_781
